# final phase output stores also use sc1 nt (on top of v70)
# baseline (speedup 1.0000x reference)
; __device__ __forceinline__ void final_phase(CArgs* a, int gw, int NGW, int lane) {
;     ...
;         for (int rr = 0; rr < 2; ++rr) { const int m = mb + rr * NGW; if (m < M) { sp[rr] = ssp[(size_t)m * 16 + (lane & 15)];
; #pragma unroll
;             for (int j = 0; j < 2; ++j) raw[rr][j] = *((const v4u*)(XB + (size_t)m * D) + lane + 64 * j); } }
; #pragma unroll
;         for (int rr = 0; rr < 2; ++rr) { const int m = mb + rr * NGW; if (m < M) { float s = sp[rr];
;             s += __shfl_xor(s, 1); s += __shfl_xor(s, 2); s += __shfl_xor(s, 4); s += __shfl_xor(s, 8);
;             const float r = __builtin_amdgcn_rsqf(s * (1.f / 1024.f) + EPS);
; #pragma unroll
;             for (int j = 0; j < 2; ++j) { const v4u w = raw[rr][j]; const int col = 8 * (lane + 64 * j);
;                 const f32x4 g0 = *(const f32x4*)(g + col), g1 = *(const f32x4*)(g + col + 4);
;                 const f32x4 v0 = (f32x4){__builtin_bit_cast(float, w.x << 16), __builtin_bit_cast(float, w.x & 0xffff0000u), __builtin_bit_cast(float, w.y << 16), __builtin_bit_cast(float, w.y & 0xffff0000u)};
;                 const f32x4 v1 = (f32x4){__builtin_bit_cast(float, w.z << 16), __builtin_bit_cast(float, w.z & 0xffff0000u), __builtin_bit_cast(float, w.w << 16), __builtin_bit_cast(float, w.w & 0xffff0000u)};
;                 __builtin_nontemporal_store(v0 * r * g0, (f32x4*)(X + (size_t)m * D + col)); __builtin_nontemporal_store(v1 * r * g1, (f32x4*)(X + (size_t)m * D + col + 4)); } } } }
.LBB0_1137:
	global_load_dwordx4 v[8:11], v[22:23], off
	global_load_dwordx4 v[12:15], v[22:23], off offset:16
	ds_bpermute_b32 v30, v18, v19
	s_ashr_i32 s1, s0, 31
	v_lshlrev_b32_e32 v32, 16, v5
	v_and_b32_e32 v35, 0xffff0000, v6
	v_lshlrev_b32_e32 v36, 16, v7
	s_waitcnt lgkmcnt(0)
	v_add_f32_e32 v30, v19, v30
	ds_bpermute_b32 v31, v26, v30
	s_lshl_b64 s[2:3], s[0:1], 12
	v_lshl_add_u64 v[40:41], v[24:25], 0, s[2:3]
	s_waitcnt lgkmcnt(0)
	v_add_f32_e32 v33, v30, v31
	ds_bpermute_b32 v34, v27, v33
	v_lshlrev_b32_e32 v30, 16, v4
	v_and_b32_e32 v31, 0xffff0000, v4
	s_waitcnt lgkmcnt(0)
	v_add_f32_e32 v37, v33, v34
	ds_bpermute_b32 v38, v28, v37
	v_and_b32_e32 v33, 0xffff0000, v5
	v_lshlrev_b32_e32 v34, 16, v6
	s_waitcnt lgkmcnt(0)
	v_add_f32_e32 v37, v37, v38
	v_fmamk_f32 v37, v37, 0x3a800000, v29
	v_rsq_f32_e32 v38, v37
	v_and_b32_e32 v37, 0xffff0000, v7
	v_pk_mul_f32 v[30:31], v[38:39], v[30:31] op_sel_hi:[0,1]
	v_pk_mul_f32 v[32:33], v[38:39], v[32:33] op_sel_hi:[0,1]
	v_pk_mul_f32 v[34:35], v[38:39], v[34:35] op_sel_hi:[0,1]
	v_pk_mul_f32 v[36:37], v[38:39], v[36:37] op_sel_hi:[0,1]
	s_waitcnt vmcnt(1)
	v_pk_mul_f32 v[10:11], v[10:11], v[32:33]
	v_pk_mul_f32 v[8:9], v[8:9], v[30:31]
	s_waitcnt vmcnt(0)
	v_pk_mul_f32 v[14:15], v[14:15], v[36:37]
	v_pk_mul_f32 v[12:13], v[12:13], v[34:35]
	global_store_dwordx4 v[40:41], v[8:11], off sc1 nt
	global_store_dwordx4 v[40:41], v[12:15], off offset:16 sc1 nt
	global_load_dwordx4 v[8:11], v[22:23], off offset:2048
	s_nop 0
	global_load_dwordx4 v[12:15], v[22:23], off offset:2064
	v_lshlrev_b32_e32 v30, 16, v0
	v_and_b32_e32 v31, 0xffff0000, v0
	v_lshlrev_b32_e32 v32, 16, v1
	v_and_b32_e32 v33, 0xffff0000, v1
	v_lshlrev_b32_e32 v34, 16, v2
	v_and_b32_e32 v35, 0xffff0000, v2
	v_lshlrev_b32_e32 v36, 16, v3
	v_and_b32_e32 v37, 0xffff0000, v3
	v_pk_mul_f32 v[32:33], v[38:39], v[32:33] op_sel_hi:[0,1]
	v_pk_mul_f32 v[30:31], v[38:39], v[30:31] op_sel_hi:[0,1]
	v_pk_mul_f32 v[36:37], v[38:39], v[36:37] op_sel_hi:[0,1]
	v_pk_mul_f32 v[34:35], v[38:39], v[34:35] op_sel_hi:[0,1]
	s_waitcnt vmcnt(1)
	v_pk_mul_f32 v[8:9], v[8:9], v[30:31]
	v_pk_mul_f32 v[10:11], v[10:11], v[32:33]
	s_waitcnt vmcnt(0)
	v_pk_mul_f32 v[12:13], v[12:13], v[34:35]
	v_pk_mul_f32 v[14:15], v[14:15], v[36:37]
	global_store_dwordx4 v[40:41], v[8:11], off offset:2048 sc1 nt
	global_store_dwordx4 v[40:41], v[12:15], off offset:2064 sc1 nt

; __device__ __forceinline__ void final_phase(CArgs* a, int gw, int NGW, int lane) {
;     ...
;         for (int rr = 0; rr < 2; ++rr) { const int m = mb + rr * NGW; if (m < M) { sp[rr] = ssp[(size_t)m * 16 + (lane & 15)];
; #pragma unroll
;             for (int j = 0; j < 2; ++j) raw[rr][j] = *((const v4u*)(XB + (size_t)m * D) + lane + 64 * j); } }
; #pragma unroll
;         for (int rr = 0; rr < 2; ++rr) { const int m = mb + rr * NGW; if (m < M) { float s = sp[rr];
;             s += __shfl_xor(s, 1); s += __shfl_xor(s, 2); s += __shfl_xor(s, 4); s += __shfl_xor(s, 8);
;             const float r = __builtin_amdgcn_rsqf(s * (1.f / 1024.f) + EPS);
; #pragma unroll
;             for (int j = 0; j < 2; ++j) { const v4u w = raw[rr][j]; const int col = 8 * (lane + 64 * j);
;                 const f32x4 g0 = *(const f32x4*)(g + col), g1 = *(const f32x4*)(g + col + 4);
;                 const f32x4 v0 = (f32x4){__builtin_bit_cast(float, w.x << 16), __builtin_bit_cast(float, w.x & 0xffff0000u), __builtin_bit_cast(float, w.y << 16), __builtin_bit_cast(float, w.y & 0xffff0000u)};
;                 const f32x4 v1 = (f32x4){__builtin_bit_cast(float, w.z << 16), __builtin_bit_cast(float, w.z & 0xffff0000u), __builtin_bit_cast(float, w.w << 16), __builtin_bit_cast(float, w.w & 0xffff0000u)};
;                 __builtin_nontemporal_store(v0 * r * g0, (f32x4*)(X + (size_t)m * D + col)); __builtin_nontemporal_store(v1 * r * g1, (f32x4*)(X + (size_t)m * D + col + 4)); } } } }
.LBB0_1141:
	s_nop 0
	global_load_dwordx4 v[32:35], v[22:23], off
	global_load_dwordx4 v[36:39], v[22:23], off offset:16
	s_waitcnt vmcnt(4)
	ds_bpermute_b32 v31, v18, v30
	s_lshl_b64 s[4:5], s[8:9], 12
	v_lshl_add_u64 v[44:45], v[24:25], 0, s[4:5]
	s_andn2_b64 vcc, exec, s[2:3]
	s_waitcnt lgkmcnt(0)
	v_add_f32_e32 v30, v30, v31
	ds_bpermute_b32 v31, v26, v30
	s_waitcnt lgkmcnt(0)
	v_add_f32_e32 v40, v30, v31
	ds_bpermute_b32 v41, v27, v40
	s_waitcnt vmcnt(3)
	v_lshlrev_b32_e32 v30, 16, v12
	v_and_b32_e32 v31, 0xffff0000, v12
	v_lshlrev_b32_e32 v12, 16, v13
	v_and_b32_e32 v13, 0xffff0000, v13
	s_waitcnt lgkmcnt(0)
	v_add_f32_e32 v42, v40, v41
	ds_bpermute_b32 v43, v28, v42
	v_lshlrev_b32_e32 v40, 16, v14
	v_and_b32_e32 v41, 0xffff0000, v14
	s_waitcnt lgkmcnt(0)
	v_add_f32_e32 v14, v42, v43
	v_fmamk_f32 v14, v14, 0x3a800000, v29
	v_rsq_f32_e32 v42, v14
	v_lshlrev_b32_e32 v14, 16, v15
	v_and_b32_e32 v15, 0xffff0000, v15
	v_pk_mul_f32 v[30:31], v[42:43], v[30:31] op_sel_hi:[0,1]
	v_pk_mul_f32 v[12:13], v[42:43], v[12:13] op_sel_hi:[0,1]
	v_pk_mul_f32 v[40:41], v[42:43], v[40:41] op_sel_hi:[0,1]
	v_pk_mul_f32 v[46:47], v[42:43], v[14:15] op_sel_hi:[0,1]
	s_waitcnt vmcnt(1)
	v_pk_mul_f32 v[14:15], v[34:35], v[12:13]
	v_pk_mul_f32 v[12:13], v[32:33], v[30:31]
	s_waitcnt vmcnt(0)
	v_pk_mul_f32 v[32:33], v[38:39], v[46:47]
	v_pk_mul_f32 v[30:31], v[36:37], v[40:41]
	global_store_dwordx4 v[44:45], v[12:15], off sc1 nt
	global_store_dwordx4 v[44:45], v[30:33], off offset:16 sc1 nt
	global_load_dwordx4 v[12:15], v[22:23], off offset:2048
	s_nop 0
	global_load_dwordx4 v[30:33], v[22:23], off offset:2064
	v_lshlrev_b32_e32 v34, 16, v8
	v_and_b32_e32 v35, 0xffff0000, v8
	v_lshlrev_b32_e32 v8, 16, v9
	v_and_b32_e32 v9, 0xffff0000, v9
	v_lshlrev_b32_e32 v36, 16, v10
	v_and_b32_e32 v37, 0xffff0000, v10
	v_lshlrev_b32_e32 v10, 16, v11
	v_and_b32_e32 v11, 0xffff0000, v11
	v_pk_mul_f32 v[38:39], v[42:43], v[8:9] op_sel_hi:[0,1]
	v_pk_mul_f32 v[8:9], v[42:43], v[34:35] op_sel_hi:[0,1]
	v_pk_mul_f32 v[34:35], v[42:43], v[10:11] op_sel_hi:[0,1]
	v_pk_mul_f32 v[36:37], v[42:43], v[36:37] op_sel_hi:[0,1]
	s_waitcnt vmcnt(1)
	v_pk_mul_f32 v[8:9], v[12:13], v[8:9]
	v_pk_mul_f32 v[10:11], v[14:15], v[38:39]
	s_waitcnt vmcnt(0)
	v_pk_mul_f32 v[12:13], v[30:31], v[36:37]
	v_pk_mul_f32 v[14:15], v[32:33], v[34:35]
	global_store_dwordx4 v[44:45], v[8:11], off offset:2048 sc1 nt
	global_store_dwordx4 v[44:45], v[12:15], off offset:2064 sc1 nt
	s_cbranch_vccnz .LBB0_1143
	s_cbranch_execnz .LBB0_1138
	s_branch .LBB0_1137
